# s_setprio role inversion A/B in the GEMM K-loop: the loading wave half holds priority 1 and the MMA cluster runs at 0 (guide 6.3: A/B the flips, never assume)
# baseline (speedup 1.0000x reference)
; #define PG8_STAGE(bufoff, gbase, voff) do { _Pragma("unroll") for (int _i = 0; _i < 2; ++_i) \
;         __builtin_amdgcn_global_load_lds((const unsigned*)((const char*)(gbase) + (voff)[_i]), (PG8_LAS unsigned*)(lds + (bufoff) + ldsw + _i * 8192), 16, 0, 0); } while (0)
; #define PG8_LDA(dst, b, h) do { _Pragma("unroll") for (int m = 0; m < 4; ++m) _Pragma("unroll") for (int k = 0; k < 2; ++k) dst[m][k] = *(const PG8_LAS bf16x8*)(lds + PG8_SA(b, h) + aoff + m * 2048 + k * 1024); } while (0)
; #define PG8_LDB(dst, b, h) do { _Pragma("unroll") for (int n = 0; n < 2; ++n) _Pragma("unroll") for (int k = 0; k < 2; ++k) dst[n][k] = *(const PG8_LAS bf16x8*)(lds + PG8_SB(b, h) + boff + n * 2048 + k * 1024); } while (0)
; #define PG8_MMA(ai, bj, At, Bt) do { __builtin_amdgcn_s_setprio(1); _Pragma("unroll") for (int m = 0; m < 4; ++m) _Pragma("unroll") for (int n = 0; n < 2; ++n) _Pragma("unroll") for (int k = 0; k < 2; ++k) \
;         acc[ai][bj][m][n] = __builtin_amdgcn_mfma_f32_16x16x32_bf16(Bt[n][k], At[m][k], acc[ai][bj][m][n], 0, 0, 0); __builtin_amdgcn_s_setprio(0); } while (0)
; #define PG8_WAIT_V(n) asm volatile("s_waitcnt vmcnt(" #n ")" ::: "memory")
; #define PG8_WAIT_L(n) asm volatile("s_waitcnt lgkmcnt(" #n ")" ::: "memory")
; #define PG8_BAR __builtin_amdgcn_s_barrier()
; #define PG8_SCHED __builtin_amdgcn_sched_barrier(0)
; template <class Epi, class Sched, bool ALIGN_EPI = false, bool SP2 = false>
; __device__ __forceinline__ void gemm_phase(PG8_LAS unsigned char* lds, const Gemm g, const Sched& S, const Epi& E) {
;     ...
;             PG8_LDB(B0, 0, 0); PG8_LDB(B1, 0, 1); PG8_SCHED; PG8_LDA(At, 0, 0); PG8_STAGE(PG8_SA(1, 1), a1 + hstep, voffA);
;             PG8_WAIT_V(8); PG8_WAIT_L(0); PG8_BAR; PG8_MMA(0, 0, At, B0); PG8_MMA(0, 1, At, B1); PG8_BAR; PG8_SCHED;
;             PG8_LDA(At, 0, 1); PG8_STAGE(PG8_SB(0, 0), b2, voffB); PG8_STAGE(PG8_SB(0, 1), b2 + hstep, voffB); PG8_STAGE(PG8_SA(0, 0), a2, voffA);
;             PG8_WAIT_V(8); PG8_WAIT_L(0); PG8_BAR; PG8_MMA(1, 0, At, B0); PG8_MMA(1, 1, At, B1); PG8_BAR; PG8_SCHED;
.LBB0_154:
	s_add_i32 s18, s14, 2
	s_add_u32 s19, s12, 0x80
	s_addc_u32 s15, s13, 0
	s_add_i32 s24, 0, 0x10000
	s_cmp_eq_u32 s91, s14
	s_cselect_b32 s15, s7, s15
	s_cselect_b32 s14, s6, s19
	v_add_u32_e32 v156, s24, v159
	s_cselect_b32 s23, s9, s11
	s_cselect_b32 s22, s8, s2
	s_add_i32 s19, 0, 0x14000
	ds_read_b128 v[170:173], v156
	ds_read_b128 v[174:177], v156 offset:1024
	ds_read_b128 v[178:181], v156 offset:2048
	ds_read_b128 v[192:195], v156 offset:3072
	v_add_u32_e32 v156, s19, v159
	ds_read_b128 v[196:199], v156
	ds_read_b128 v[200:203], v156 offset:1024
	ds_read_b128 v[204:207], v156 offset:2048
	ds_read_b128 v[208:211], v156 offset:3072
	v_lshl_add_u64 v[156:157], s[12:13], 0, v[152:153]
	s_add_i32 m0, s82, 0xc000
	ds_read_b128 v[212:215], v168
	ds_read_b128 v[216:219], v168 offset:1024
	ds_read_b128 v[220:223], v168 offset:2048
	ds_read_b128 v[224:227], v168 offset:3072
	ds_read_b128 v[228:231], v168 offset:4096
	ds_read_b128 v[232:235], v168 offset:5120
	ds_read_b128 v[236:239], v168 offset:6144
	ds_read_b128 v[240:243], v168 offset:7168
	global_load_lds_dwordx4 v[156:157], off
	v_lshl_add_u64 v[156:157], s[12:13], 0, v[154:155]
	s_add_i32 m0, s82, 0xe000
	s_nop 0
	global_load_lds_dwordx4 v[156:157], off
	s_waitcnt vmcnt(8)
	s_waitcnt lgkmcnt(0)
	s_barrier
	s_setprio 0
	s_waitcnt lgkmcnt(0)
	v_mfma_f32_16x16x32_bf16 v[126:129], v[170:173], v[212:215], v[126:129]
	v_mfma_f32_16x16x32_bf16 v[122:125], v[178:181], v[212:215], v[122:125]
	v_mfma_f32_16x16x32_bf16 v[118:121], v[170:173], v[220:223], v[118:121]
	v_mfma_f32_16x16x32_bf16 v[114:117], v[178:181], v[220:223], v[114:117]
	v_mfma_f32_16x16x32_bf16 v[110:113], v[170:173], v[228:231], v[110:113]
	v_mfma_f32_16x16x32_bf16 v[106:109], v[178:181], v[228:231], v[106:109]
	v_mfma_f32_16x16x32_bf16 v[102:105], v[170:173], v[236:239], v[102:105]
	v_mfma_f32_16x16x32_bf16 v[98:101], v[178:181], v[236:239], v[98:101]
	v_mfma_f32_16x16x32_bf16 v[126:129], v[174:177], v[216:219], v[126:129]
	v_mfma_f32_16x16x32_bf16 v[122:125], v[192:195], v[216:219], v[122:125]
	v_mfma_f32_16x16x32_bf16 v[118:121], v[174:177], v[224:227], v[118:121]
	v_mfma_f32_16x16x32_bf16 v[114:117], v[192:195], v[224:227], v[114:117]
	v_mfma_f32_16x16x32_bf16 v[110:113], v[174:177], v[232:235], v[110:113]
	v_mfma_f32_16x16x32_bf16 v[106:109], v[192:195], v[232:235], v[106:109]
	v_mfma_f32_16x16x32_bf16 v[102:105], v[174:177], v[240:243], v[102:105]
	v_mfma_f32_16x16x32_bf16 v[98:101], v[192:195], v[240:243], v[98:101]
	s_setprio 1
	s_setprio 0
	v_mfma_f32_16x16x32_bf16 v[62:65], v[196:199], v[212:215], v[62:65]
	v_mfma_f32_16x16x32_bf16 v[58:61], v[204:207], v[212:215], v[58:61]
	v_mfma_f32_16x16x32_bf16 v[54:57], v[196:199], v[220:223], v[54:57]
	v_mfma_f32_16x16x32_bf16 v[50:53], v[204:207], v[220:223], v[50:53]
	v_mfma_f32_16x16x32_bf16 v[46:49], v[196:199], v[228:231], v[46:49]
	v_mfma_f32_16x16x32_bf16 v[42:45], v[204:207], v[228:231], v[42:45]
	v_mfma_f32_16x16x32_bf16 v[38:41], v[196:199], v[236:239], v[38:41]
	v_mfma_f32_16x16x32_bf16 v[34:37], v[204:207], v[236:239], v[34:37]
	v_mfma_f32_16x16x32_bf16 v[62:65], v[200:203], v[216:219], v[62:65]
	v_mfma_f32_16x16x32_bf16 v[58:61], v[208:211], v[216:219], v[58:61]
	v_mfma_f32_16x16x32_bf16 v[54:57], v[200:203], v[224:227], v[54:57]
	v_mfma_f32_16x16x32_bf16 v[50:53], v[208:211], v[224:227], v[50:53]
	v_mfma_f32_16x16x32_bf16 v[46:49], v[200:203], v[232:235], v[46:49]
	v_mfma_f32_16x16x32_bf16 v[42:45], v[208:211], v[232:235], v[42:45]
	v_mfma_f32_16x16x32_bf16 v[38:41], v[200:203], v[240:243], v[38:41]
	v_mfma_f32_16x16x32_bf16 v[34:37], v[208:211], v[240:243], v[34:37]
	s_setprio 1
	s_barrier
	s_add_i32 s24, s24, s69
	v_lshl_add_u64 v[156:157], s[22:23], 0, v[0:1]
	s_mov_b32 m0, s24
	ds_read_b128 v[212:215], v168 offset:16384
	ds_read_b128 v[216:219], v168 offset:17408
	ds_read_b128 v[220:223], v168 offset:18432
	ds_read_b128 v[224:227], v168 offset:19456
	ds_read_b128 v[228:231], v168 offset:20480
	ds_read_b128 v[232:235], v168 offset:21504
	ds_read_b128 v[236:239], v168 offset:22528
	ds_read_b128 v[240:243], v168 offset:23552
	global_load_lds_dwordx4 v[156:157], off
	s_add_i32 m0, s24, 0x2000
	v_lshl_add_u64 v[182:183], s[22:23], 0, v[134:135]
	s_add_u32 s22, s22, s78
	s_addc_u32 s23, s23, 0
	s_add_i32 s19, s19, s69
	global_load_lds_dwordx4 v[182:183], off
	v_lshl_add_u64 v[244:245], s[22:23], 0, v[0:1]
	s_mov_b32 m0, s19
	v_lshl_add_u64 v[246:247], s[22:23], 0, v[134:135]
	global_load_lds_dwordx4 v[244:245], off
	s_add_i32 m0, s19, 0x2000
	v_lshl_add_u64 v[248:249], s[14:15], 0, v[130:131]
	global_load_lds_dwordx4 v[246:247], off
	s_mov_b32 m0, s82
	v_lshl_add_u64 v[250:251], s[14:15], 0, v[132:133]
	global_load_lds_dwordx4 v[248:249], off
	s_mov_b32 m0, s66
	s_nop 0
	global_load_lds_dwordx4 v[250:251], off
	s_waitcnt vmcnt(8)
	s_waitcnt lgkmcnt(0)
	s_barrier
; #define PG8_STAGE(bufoff, gbase, voff) do { _Pragma("unroll") for (int _i = 0; _i < 2; ++_i) \
;         __builtin_amdgcn_global_load_lds((const unsigned*)((const char*)(gbase) + (voff)[_i]), (PG8_LAS unsigned*)(lds + (bufoff) + ldsw + _i * 8192), 16, 0, 0); } while (0)
; #define PG8_LDA(dst, b, h) do { _Pragma("unroll") for (int m = 0; m < 4; ++m) _Pragma("unroll") for (int k = 0; k < 2; ++k) dst[m][k] = *(const PG8_LAS bf16x8*)(lds + PG8_SA(b, h) + aoff + m * 2048 + k * 1024); } while (0)
; #define PG8_LDB(dst, b, h) do { _Pragma("unroll") for (int n = 0; n < 2; ++n) _Pragma("unroll") for (int k = 0; k < 2; ++k) dst[n][k] = *(const PG8_LAS bf16x8*)(lds + PG8_SB(b, h) + boff + n * 2048 + k * 1024); } while (0)
; #define PG8_MMA(ai, bj, At, Bt) do { __builtin_amdgcn_s_setprio(1); _Pragma("unroll") for (int m = 0; m < 4; ++m) _Pragma("unroll") for (int n = 0; n < 2; ++n) _Pragma("unroll") for (int k = 0; k < 2; ++k) \
;         acc[ai][bj][m][n] = __builtin_amdgcn_mfma_f32_16x16x32_bf16(Bt[n][k], At[m][k], acc[ai][bj][m][n], 0, 0, 0); __builtin_amdgcn_s_setprio(0); } while (0)
; #define PG8_WAIT_V(n) asm volatile("s_waitcnt vmcnt(" #n ")" ::: "memory")
; #define PG8_WAIT_L(n) asm volatile("s_waitcnt lgkmcnt(" #n ")" ::: "memory")
; #define PG8_BAR __builtin_amdgcn_s_barrier()
; #define PG8_SCHED __builtin_amdgcn_sched_barrier(0)
; template <class Epi, class Sched, bool ALIGN_EPI = false, bool SP2 = false>
; __device__ __forceinline__ void gemm_phase(PG8_LAS unsigned char* lds, const Gemm g, const Sched& S, const Epi& E) {
;     ...
;             PG8_WAIT_V(8); PG8_WAIT_L(0); PG8_BAR; PG8_MMA(1, 0, At, B0); PG8_MMA(1, 1, At, B1); PG8_BAR; PG8_SCHED;
;             PG8_LDB(B0, 1, 0); PG8_LDB(B1, 1, 1); PG8_SCHED; PG8_LDA(At, 1, 0); PG8_STAGE(PG8_SA(0, 1), a2 + hstep, voffA);
;             PG8_WAIT_V(8); PG8_WAIT_L(0); PG8_BAR; PG8_MMA(0, 0, At, B0); PG8_MMA(0, 1, At, B1); PG8_BAR; PG8_SCHED;
	s_setprio 0
	s_waitcnt lgkmcnt(0)
	v_mfma_f32_16x16x32_bf16 v[94:97], v[170:173], v[212:215], v[94:97]
	v_mfma_f32_16x16x32_bf16 v[90:93], v[178:181], v[212:215], v[90:93]
	v_mfma_f32_16x16x32_bf16 v[86:89], v[170:173], v[220:223], v[86:89]
	v_mfma_f32_16x16x32_bf16 v[82:85], v[178:181], v[220:223], v[82:85]
	v_mfma_f32_16x16x32_bf16 v[78:81], v[170:173], v[228:231], v[78:81]
	v_mfma_f32_16x16x32_bf16 v[74:77], v[178:181], v[228:231], v[74:77]
	v_mfma_f32_16x16x32_bf16 v[70:73], v[170:173], v[236:239], v[70:73]
	v_mfma_f32_16x16x32_bf16 v[66:69], v[178:181], v[236:239], v[66:69]
	v_mfma_f32_16x16x32_bf16 v[94:97], v[174:177], v[216:219], v[94:97]
	v_mfma_f32_16x16x32_bf16 v[90:93], v[192:195], v[216:219], v[90:93]
	v_mfma_f32_16x16x32_bf16 v[86:89], v[174:177], v[224:227], v[86:89]
	v_mfma_f32_16x16x32_bf16 v[82:85], v[192:195], v[224:227], v[82:85]
	v_mfma_f32_16x16x32_bf16 v[78:81], v[174:177], v[232:235], v[78:81]
	v_mfma_f32_16x16x32_bf16 v[74:77], v[192:195], v[232:235], v[74:77]
	v_mfma_f32_16x16x32_bf16 v[70:73], v[174:177], v[240:243], v[70:73]
	v_mfma_f32_16x16x32_bf16 v[66:69], v[192:195], v[240:243], v[66:69]
	s_setprio 1
	s_setprio 0
	v_mfma_f32_16x16x32_bf16 v[30:33], v[196:199], v[212:215], v[30:33]
	v_mfma_f32_16x16x32_bf16 v[26:29], v[204:207], v[212:215], v[26:29]
	v_mfma_f32_16x16x32_bf16 v[22:25], v[196:199], v[220:223], v[22:25]
	v_mfma_f32_16x16x32_bf16 v[18:21], v[204:207], v[220:223], v[18:21]
	v_mfma_f32_16x16x32_bf16 v[14:17], v[196:199], v[228:231], v[14:17]
	v_mfma_f32_16x16x32_bf16 v[10:13], v[204:207], v[228:231], v[10:13]
	v_mfma_f32_16x16x32_bf16 v[6:9], v[196:199], v[236:239], v[6:9]
	v_mfma_f32_16x16x32_bf16 v[2:5], v[204:207], v[236:239], v[2:5]
	v_mfma_f32_16x16x32_bf16 v[30:33], v[200:203], v[216:219], v[30:33]
	v_mfma_f32_16x16x32_bf16 v[26:29], v[208:211], v[216:219], v[26:29]
	v_mfma_f32_16x16x32_bf16 v[22:25], v[200:203], v[224:227], v[22:25]
	v_mfma_f32_16x16x32_bf16 v[18:21], v[208:211], v[224:227], v[18:21]
	v_mfma_f32_16x16x32_bf16 v[14:17], v[200:203], v[232:235], v[14:17]
	v_mfma_f32_16x16x32_bf16 v[10:13], v[208:211], v[232:235], v[10:13]
	v_mfma_f32_16x16x32_bf16 v[6:9], v[200:203], v[240:243], v[6:9]
	v_mfma_f32_16x16x32_bf16 v[2:5], v[208:211], v[240:243], v[2:5]
	s_setprio 1
	s_barrier
	s_add_i32 s19, 0, 0x18000
	v_add_u32_e32 v169, s19, v159
	s_add_i32 s22, 0, 0x1c000
	ds_read_b128 v[170:173], v169
	ds_read_b128 v[174:177], v169 offset:1024
	ds_read_b128 v[178:181], v169 offset:2048
	ds_read_b128 v[192:195], v169 offset:3072
	v_add_u32_e32 v169, s22, v159
	ds_read_b128 v[196:199], v169
	ds_read_b128 v[200:203], v169 offset:1024
	ds_read_b128 v[204:207], v169 offset:2048
	ds_read_b128 v[208:211], v169 offset:3072
	s_add_u32 s14, s14, s78
	s_addc_u32 s15, s15, 0
	s_mov_b32 m0, s67
	v_lshl_add_u64 v[252:253], s[14:15], 0, v[130:131]
	ds_read_b128 v[212:215], v168 offset:32768
	ds_read_b128 v[216:219], v168 offset:33792
	ds_read_b128 v[220:223], v168 offset:34816
	ds_read_b128 v[224:227], v168 offset:35840
	ds_read_b128 v[228:231], v168 offset:36864
	ds_read_b128 v[232:235], v168 offset:37888
	ds_read_b128 v[236:239], v168 offset:38912
	ds_read_b128 v[240:243], v168 offset:39936
	global_load_lds_dwordx4 v[252:253], off
	v_lshl_add_u64 v[252:253], s[14:15], 0, v[132:133]
	s_mov_b32 m0, s45
	s_nop 0
	global_load_lds_dwordx4 v[252:253], off
	s_waitcnt vmcnt(8)
	s_waitcnt lgkmcnt(0)
	s_barrier
	s_setprio 0
	s_waitcnt lgkmcnt(0)
	v_mfma_f32_16x16x32_bf16 v[126:129], v[170:173], v[212:215], v[126:129]
	v_mfma_f32_16x16x32_bf16 v[122:125], v[178:181], v[212:215], v[122:125]
	v_mfma_f32_16x16x32_bf16 v[118:121], v[170:173], v[220:223], v[118:121]
	v_mfma_f32_16x16x32_bf16 v[114:117], v[178:181], v[220:223], v[114:117]
	v_mfma_f32_16x16x32_bf16 v[110:113], v[170:173], v[228:231], v[110:113]
	v_mfma_f32_16x16x32_bf16 v[106:109], v[178:181], v[228:231], v[106:109]
	v_mfma_f32_16x16x32_bf16 v[102:105], v[170:173], v[236:239], v[102:105]
	v_mfma_f32_16x16x32_bf16 v[98:101], v[178:181], v[236:239], v[98:101]
	v_mfma_f32_16x16x32_bf16 v[126:129], v[174:177], v[216:219], v[126:129]
	v_mfma_f32_16x16x32_bf16 v[122:125], v[192:195], v[216:219], v[122:125]
	v_mfma_f32_16x16x32_bf16 v[118:121], v[174:177], v[224:227], v[118:121]
	v_mfma_f32_16x16x32_bf16 v[114:117], v[192:195], v[224:227], v[114:117]
	v_mfma_f32_16x16x32_bf16 v[110:113], v[174:177], v[232:235], v[110:113]
	v_mfma_f32_16x16x32_bf16 v[106:109], v[192:195], v[232:235], v[106:109]
	v_mfma_f32_16x16x32_bf16 v[102:105], v[174:177], v[240:243], v[102:105]
	v_mfma_f32_16x16x32_bf16 v[98:101], v[192:195], v[240:243], v[98:101]
	s_setprio 1
	s_setprio 0
	v_mfma_f32_16x16x32_bf16 v[62:65], v[196:199], v[212:215], v[62:65]
	v_mfma_f32_16x16x32_bf16 v[58:61], v[204:207], v[212:215], v[58:61]
	v_mfma_f32_16x16x32_bf16 v[54:57], v[196:199], v[220:223], v[54:57]
	v_mfma_f32_16x16x32_bf16 v[50:53], v[204:207], v[220:223], v[50:53]
	v_mfma_f32_16x16x32_bf16 v[46:49], v[196:199], v[228:231], v[46:49]
	v_mfma_f32_16x16x32_bf16 v[42:45], v[204:207], v[228:231], v[42:45]
	v_mfma_f32_16x16x32_bf16 v[38:41], v[196:199], v[236:239], v[38:41]
	v_mfma_f32_16x16x32_bf16 v[34:37], v[204:207], v[236:239], v[34:37]
	v_mfma_f32_16x16x32_bf16 v[62:65], v[200:203], v[216:219], v[62:65]
	v_mfma_f32_16x16x32_bf16 v[58:61], v[208:211], v[216:219], v[58:61]
	v_mfma_f32_16x16x32_bf16 v[54:57], v[200:203], v[224:227], v[54:57]
	v_mfma_f32_16x16x32_bf16 v[50:53], v[208:211], v[224:227], v[50:53]
	v_mfma_f32_16x16x32_bf16 v[46:49], v[200:203], v[232:235], v[46:49]
	v_mfma_f32_16x16x32_bf16 v[42:45], v[208:211], v[232:235], v[42:45]
	v_mfma_f32_16x16x32_bf16 v[38:41], v[200:203], v[240:243], v[38:41]
	v_mfma_f32_16x16x32_bf16 v[34:37], v[208:211], v[240:243], v[34:37]
	s_setprio 1
	s_barrier
; #define PG8_STAGE(bufoff, gbase, voff) do { _Pragma("unroll") for (int _i = 0; _i < 2; ++_i) \
;         __builtin_amdgcn_global_load_lds((const unsigned*)((const char*)(gbase) + (voff)[_i]), (PG8_LAS unsigned*)(lds + (bufoff) + ldsw + _i * 8192), 16, 0, 0); } while (0)
; #define PG8_LDA(dst, b, h) do { _Pragma("unroll") for (int m = 0; m < 4; ++m) _Pragma("unroll") for (int k = 0; k < 2; ++k) dst[m][k] = *(const PG8_LAS bf16x8*)(lds + PG8_SA(b, h) + aoff + m * 2048 + k * 1024); } while (0)
; #define PG8_MMA(ai, bj, At, Bt) do { __builtin_amdgcn_s_setprio(1); _Pragma("unroll") for (int m = 0; m < 4; ++m) _Pragma("unroll") for (int n = 0; n < 2; ++n) _Pragma("unroll") for (int k = 0; k < 2; ++k) \
;         acc[ai][bj][m][n] = __builtin_amdgcn_mfma_f32_16x16x32_bf16(Bt[n][k], At[m][k], acc[ai][bj][m][n], 0, 0, 0); __builtin_amdgcn_s_setprio(0); } while (0)
; #define PG8_WAIT_V(n) asm volatile("s_waitcnt vmcnt(" #n ")" ::: "memory")
; #define PG8_WAIT_L(n) asm volatile("s_waitcnt lgkmcnt(" #n ")" ::: "memory")
; #define PG8_BAR __builtin_amdgcn_s_barrier()
; #define PG8_SCHED __builtin_amdgcn_sched_barrier(0)
; template <class Epi, class Sched, bool ALIGN_EPI = false, bool SP2 = false>
; __device__ __forceinline__ void gemm_phase(PG8_LAS unsigned char* lds, const Gemm g, const Sched& S, const Epi& E) {
;     ...
;             PG8_LDA(At, 1, 1); PG8_STAGE(PG8_SB(1, 0), b3, voffB); PG8_STAGE(PG8_SB(1, 1), b3 + hstep, voffB); PG8_STAGE(PG8_SA(1, 0), a3, voffA);
;             PG8_WAIT_V(8); PG8_WAIT_L(0); PG8_BAR; PG8_MMA(1, 0, At, B0); PG8_MMA(1, 1, At, B1); PG8_BAR; PG8_SCHED;
;     ...
;         }
;         if constexpr (ALIGN_EPI) { if (wr == 0) PG8_BAR; }
	s_add_i32 s14, s19, s69
	v_lshl_add_u64 v[156:157], v[156:157], 0, s[92:93]
	s_mov_b32 m0, s14
	ds_read_b128 v[212:215], v168 offset:49152
	ds_read_b128 v[216:219], v168 offset:50176
	ds_read_b128 v[220:223], v168 offset:51200
	ds_read_b128 v[224:227], v168 offset:52224
	ds_read_b128 v[228:231], v168 offset:53248
	ds_read_b128 v[232:235], v168 offset:54272
	ds_read_b128 v[236:239], v168 offset:55296
	ds_read_b128 v[240:243], v168 offset:56320
	global_load_lds_dwordx4 v[156:157], off
	v_lshl_add_u64 v[156:157], v[182:183], 0, s[92:93]
	s_add_i32 m0, s14, 0x2000
	s_add_i32 s14, s22, s69
	global_load_lds_dwordx4 v[156:157], off
	v_lshl_add_u64 v[156:157], v[244:245], 0, s[92:93]
	s_mov_b32 m0, s14
	s_nop 0
	global_load_lds_dwordx4 v[156:157], off
	v_lshl_add_u64 v[156:157], v[246:247], 0, s[92:93]
	s_add_i32 m0, s14, 0x2000
	s_nop 0
	global_load_lds_dwordx4 v[156:157], off
	v_lshl_add_u64 v[156:157], v[248:249], 0, s[92:93]
	s_mov_b32 m0, s36
	s_nop 0
	global_load_lds_dwordx4 v[156:157], off
	v_lshl_add_u64 v[156:157], v[250:251], 0, s[92:93]
	s_mov_b32 m0, s35
	s_nop 0
	global_load_lds_dwordx4 v[156:157], off
	s_waitcnt vmcnt(8)
	s_waitcnt lgkmcnt(0)
	s_barrier
	s_setprio 0
	s_waitcnt lgkmcnt(0)
	v_mfma_f32_16x16x32_bf16 v[94:97], v[170:173], v[212:215], v[94:97]
	v_mfma_f32_16x16x32_bf16 v[90:93], v[178:181], v[212:215], v[90:93]
	v_mfma_f32_16x16x32_bf16 v[86:89], v[170:173], v[220:223], v[86:89]
	v_mfma_f32_16x16x32_bf16 v[82:85], v[178:181], v[220:223], v[82:85]
	v_mfma_f32_16x16x32_bf16 v[78:81], v[170:173], v[228:231], v[78:81]
	v_mfma_f32_16x16x32_bf16 v[74:77], v[178:181], v[228:231], v[74:77]
	v_mfma_f32_16x16x32_bf16 v[70:73], v[170:173], v[236:239], v[70:73]
	v_mfma_f32_16x16x32_bf16 v[66:69], v[178:181], v[236:239], v[66:69]
	v_mfma_f32_16x16x32_bf16 v[94:97], v[174:177], v[216:219], v[94:97]
	v_mfma_f32_16x16x32_bf16 v[90:93], v[192:195], v[216:219], v[90:93]
	v_mfma_f32_16x16x32_bf16 v[86:89], v[174:177], v[224:227], v[86:89]
	v_mfma_f32_16x16x32_bf16 v[82:85], v[192:195], v[224:227], v[82:85]
	v_mfma_f32_16x16x32_bf16 v[78:81], v[174:177], v[232:235], v[78:81]
	v_mfma_f32_16x16x32_bf16 v[74:77], v[192:195], v[232:235], v[74:77]
	v_mfma_f32_16x16x32_bf16 v[70:73], v[174:177], v[240:243], v[70:73]
	v_mfma_f32_16x16x32_bf16 v[66:69], v[192:195], v[240:243], v[66:69]
	s_setprio 1
	s_setprio 0
	v_mfma_f32_16x16x32_bf16 v[30:33], v[196:199], v[212:215], v[30:33]
	v_mfma_f32_16x16x32_bf16 v[26:29], v[204:207], v[212:215], v[26:29]
	v_mfma_f32_16x16x32_bf16 v[22:25], v[196:199], v[220:223], v[22:25]
	v_mfma_f32_16x16x32_bf16 v[18:21], v[204:207], v[220:223], v[18:21]
	v_mfma_f32_16x16x32_bf16 v[14:17], v[196:199], v[228:231], v[14:17]
	v_mfma_f32_16x16x32_bf16 v[10:13], v[204:207], v[228:231], v[10:13]
	v_mfma_f32_16x16x32_bf16 v[6:9], v[196:199], v[236:239], v[6:9]
	v_mfma_f32_16x16x32_bf16 v[2:5], v[204:207], v[236:239], v[2:5]
	v_mfma_f32_16x16x32_bf16 v[30:33], v[200:203], v[216:219], v[30:33]
	v_mfma_f32_16x16x32_bf16 v[26:29], v[208:211], v[216:219], v[26:29]
	v_mfma_f32_16x16x32_bf16 v[22:25], v[200:203], v[224:227], v[22:25]
	v_mfma_f32_16x16x32_bf16 v[18:21], v[208:211], v[224:227], v[18:21]
	v_mfma_f32_16x16x32_bf16 v[14:17], v[200:203], v[232:235], v[14:17]
	v_mfma_f32_16x16x32_bf16 v[10:13], v[208:211], v[232:235], v[10:13]
	v_mfma_f32_16x16x32_bf16 v[6:9], v[200:203], v[240:243], v[6:9]
	v_mfma_f32_16x16x32_bf16 v[2:5], v[208:211], v[240:243], v[2:5]
	s_setprio 1
	s_barrier
	s_add_u32 s12, s12, 0x100
	s_addc_u32 s13, s13, 0
	s_add_u32 s2, s2, 0x100
	s_addc_u32 s11, s11, 0
	s_cmp_ge_u32 s18, s81
	s_mov_b32 s14, s18
	s_cbranch_scc0 .LBB0_154
	s_and_b64 vcc, exec, s[56:57]
	s_cbranch_vccz .LBB0_157
	s_barrier
